# speedup vs baseline: 1.0237x; 1.0108x over previous
; template <bool ATRANS = false, bool SWAP = true>
; DEV void gemm_seg(f32x4 (&acc)[4][4], bf16_t* As, bf16_t* Bs, const bf16_t* A, const bf16_t* B, int lda, int ldb,
;                   int K, int arow_lo, int arow_hi) {
;     ...
;   GLOAD(0, 0);
;   GLOAD(1, 1);
;   STAB(0, 0);
;   GLOAD(0, 2);
;   for (int kt = 0; kt < nk; kt += 2) {
;     COMPUTE(kt);
;     STAB(1, kt + 1);
;     GLOAD(1, kt + 3);
;     if (kt + 1 >= nk) break;
;     COMPUTE(kt + 1);
;     STAB(0, kt + 2);
;     GLOAD(0, kt + 4);
.Lvm_win1_ok:
	s_setprio 1
	ds_read_b128 v[208:211], v137
	ds_read_b128 v[212:215], v139 offset:36864
	ds_read_b128 v[220:223], v139 offset:38912
	ds_read_b128 v[224:227], v139 offset:40960
	ds_read_b128 v[228:231], v139 offset:43008
	ds_read_b128 v[232:235], v137 offset:2048
	ds_read_b128 v[236:239], v137 offset:4096
	ds_read_b128 v[240:243], v137 offset:6144
	s_waitcnt lgkmcnt(6)
	v_mfma_f32_16x16x32_bf16 v[124:127], v[212:215], v[208:211], v[124:127]
	ds_read_b128 v[244:247], v145
	ds_read_b128 v[248:251], v207 offset:36864
	s_waitcnt lgkmcnt(7)
	v_mfma_f32_16x16x32_bf16 v[120:123], v[220:223], v[208:211], v[120:123]
	s_waitcnt lgkmcnt(6)
	v_mfma_f32_16x16x32_bf16 v[116:119], v[224:227], v[208:211], v[116:119]
	s_waitcnt lgkmcnt(5)
	v_mfma_f32_16x16x32_bf16 v[112:115], v[228:231], v[208:211], v[112:115]
	ds_read_b128 v[208:211], v207 offset:38912
	s_waitcnt lgkmcnt(5)
	v_mfma_f32_16x16x32_bf16 v[108:111], v[212:215], v[232:235], v[108:111]
	v_mfma_f32_16x16x32_bf16 v[104:107], v[220:223], v[232:235], v[104:107]
	v_mfma_f32_16x16x32_bf16 v[100:103], v[224:227], v[232:235], v[100:103]
	v_mfma_f32_16x16x32_bf16 v[96:99], v[228:231], v[232:235], v[96:99]
	ds_read_b128 v[232:235], v207 offset:40960
	s_waitcnt lgkmcnt(5)
	v_mfma_f32_16x16x32_bf16 v[92:95], v[212:215], v[236:239], v[92:95]
	v_mfma_f32_16x16x32_bf16 v[88:91], v[220:223], v[236:239], v[88:91]
	v_mfma_f32_16x16x32_bf16 v[84:87], v[224:227], v[236:239], v[84:87]
	v_mfma_f32_16x16x32_bf16 v[80:83], v[228:231], v[236:239], v[80:83]
	ds_read_b128 v[236:239], v207 offset:43008
	s_waitcnt lgkmcnt(5)
	v_mfma_f32_16x16x32_bf16 v[76:79], v[212:215], v[240:243], v[76:79]
	ds_read_b128 v[212:215], v145 offset:2048
	v_mfma_f32_16x16x32_bf16 v[72:75], v[220:223], v[240:243], v[72:75]
	ds_read_b128 v[220:223], v145 offset:4096
	v_mfma_f32_16x16x32_bf16 v[68:71], v[224:227], v[240:243], v[68:71]
	ds_read_b128 v[224:227], v145 offset:6144
	v_mfma_f32_16x16x32_bf16 v[64:67], v[228:231], v[240:243], v[64:67]
	s_waitcnt vmcnt(8)
	ds_write_b128 v133, v[0:3] offset:18432
	s_waitcnt lgkmcnt(7)
	v_mfma_f32_16x16x32_bf16 v[124:127], v[248:251], v[244:247], v[124:127]
	s_waitcnt lgkmcnt(6)
	v_mfma_f32_16x16x32_bf16 v[120:123], v[208:211], v[244:247], v[120:123]
	ds_write_b128 v133, v[4:7] offset:22528
	s_waitcnt lgkmcnt(6)
	v_mfma_f32_16x16x32_bf16 v[116:119], v[232:235], v[244:247], v[116:119]
	s_waitcnt lgkmcnt(5)
	v_mfma_f32_16x16x32_bf16 v[112:115], v[236:239], v[244:247], v[112:115]
	ds_write_b128 v133, v[8:11] offset:26624
	s_waitcnt lgkmcnt(5)
	v_mfma_f32_16x16x32_bf16 v[108:111], v[248:251], v[212:215], v[108:111]
	v_mfma_f32_16x16x32_bf16 v[104:107], v[208:211], v[212:215], v[104:107]
	ds_write_b128 v133, v[12:15] offset:30720
	v_mfma_f32_16x16x32_bf16 v[100:103], v[232:235], v[212:215], v[100:103]
	v_mfma_f32_16x16x32_bf16 v[96:99], v[236:239], v[212:215], v[96:99]
	ds_write_b128 v133, v[16:19] offset:55296
	s_waitcnt lgkmcnt(6)
	v_mfma_f32_16x16x32_bf16 v[92:95], v[248:251], v[220:223], v[92:95]
	v_mfma_f32_16x16x32_bf16 v[88:91], v[208:211], v[220:223], v[88:91]
	ds_write_b128 v133, v[20:23] offset:59392
	v_mfma_f32_16x16x32_bf16 v[84:87], v[232:235], v[220:223], v[84:87]
	v_mfma_f32_16x16x32_bf16 v[80:83], v[236:239], v[220:223], v[80:83]
	ds_write_b128 v133, v[24:27] offset:63488
	s_waitcnt lgkmcnt(7)
	v_mfma_f32_16x16x32_bf16 v[76:79], v[248:251], v[224:227], v[76:79]
	v_mfma_f32_16x16x32_bf16 v[72:75], v[208:211], v[224:227], v[72:75]
	ds_write_b128 v135, v[32:35] offset:12288
	v_mfma_f32_16x16x32_bf16 v[68:71], v[232:235], v[224:227], v[68:71]
	v_mfma_f32_16x16x32_bf16 v[64:67], v[236:239], v[224:227], v[64:67]
	s_setprio 0
	s_cmp_gt_u32 s19, 12
	v_lshl_add_u64 v[164:165], v[146:147], 0, v[128:129]
	v_lshl_add_u64 v[162:163], v[148:149], 0, v[128:129]
	v_lshl_add_u64 v[160:161], v[150:151], 0, v[128:129]
	v_lshl_add_u64 v[158:159], v[152:153], 0, v[128:129]
	v_lshl_add_u64 v[156:157], v[154:155], 0, v[128:129]
	s_waitcnt lgkmcnt(0)
	s_barrier
	s_cbranch_scc1 .LBB0_333
	v_add_co_u32_e32 v20, vcc, 0x10000, v156
	global_load_dwordx4 v[0:3], v[164:165], off offset:384
	global_load_dwordx4 v[4:7], v[162:163], off offset:384
	global_load_dwordx4 v[8:11], v[160:161], off offset:384
	global_load_dwordx4 v[12:15], v[158:159], off offset:384
	global_load_dwordx4 v[16:19], v[156:157], off offset:384
	v_addc_co_u32_e32 v21, vcc, 0, v157, vcc
	v_add_co_u32_e32 v24, vcc, 0x20000, v156
	s_nop 1
	v_addc_co_u32_e32 v25, vcc, 0, v157, vcc
	v_add_co_u32_e32 v32, vcc, 0x30000, v156
	global_load_dwordx4 v[20:23], v[20:21], off offset:384
	s_nop 0
	global_load_dwordx4 v[24:27], v[24:25], off offset:384
	v_addc_co_u32_e32 v33, vcc, 0, v157, vcc
	global_load_dwordx4 v[32:35], v[32:33], off offset:384
; template <bool ATRANS = false, bool SWAP = true>
; DEV void gemm_seg(f32x4 (&acc)[4][4], bf16_t* As, bf16_t* Bs, const bf16_t* A, const bf16_t* B, int lda, int ldb,
;                   int K, int arow_lo, int arow_hi) {
;     ...
;   GLOAD(0, 0);
;   GLOAD(1, 1);
;   STAB(0, 0);
;   GLOAD(0, 2);
;   for (int kt = 0; kt < nk; kt += 2) {
;     COMPUTE(kt);
;     STAB(1, kt + 1);
;     GLOAD(1, kt + 3);
;     if (kt + 1 >= nk) break;
;     COMPUTE(kt + 1);
;     STAB(0, kt + 2);
.LBB0_333:
	s_setprio 1
	ds_read_b128 v[208:211], v137 offset:18432
	ds_read_b128 v[212:215], v139 offset:55296
	ds_read_b128 v[220:223], v139 offset:57344
	ds_read_b128 v[224:227], v139 offset:59392
	ds_read_b128 v[228:231], v139 offset:61440
	ds_read_b128 v[232:235], v137 offset:20480
	ds_read_b128 v[236:239], v137 offset:22528
	ds_read_b128 v[240:243], v137 offset:24576
	s_waitcnt lgkmcnt(6)
	v_mfma_f32_16x16x32_bf16 v[124:127], v[212:215], v[208:211], v[124:127]
	ds_read_b128 v[244:247], v145 offset:18432
	ds_read_b128 v[248:251], v207 offset:55296
	s_waitcnt lgkmcnt(7)
	v_mfma_f32_16x16x32_bf16 v[120:123], v[220:223], v[208:211], v[120:123]
	s_waitcnt lgkmcnt(6)
	v_mfma_f32_16x16x32_bf16 v[116:119], v[224:227], v[208:211], v[116:119]
	s_waitcnt lgkmcnt(5)
	v_mfma_f32_16x16x32_bf16 v[112:115], v[228:231], v[208:211], v[112:115]
	ds_read_b128 v[208:211], v207 offset:57344
	s_waitcnt lgkmcnt(5)
	v_mfma_f32_16x16x32_bf16 v[108:111], v[212:215], v[232:235], v[108:111]
	v_mfma_f32_16x16x32_bf16 v[104:107], v[220:223], v[232:235], v[104:107]
	v_mfma_f32_16x16x32_bf16 v[100:103], v[224:227], v[232:235], v[100:103]
	v_mfma_f32_16x16x32_bf16 v[96:99], v[228:231], v[232:235], v[96:99]
	ds_read_b128 v[232:235], v207 offset:59392
	s_waitcnt lgkmcnt(5)
	v_mfma_f32_16x16x32_bf16 v[92:95], v[212:215], v[236:239], v[92:95]
	v_mfma_f32_16x16x32_bf16 v[88:91], v[220:223], v[236:239], v[88:91]
	v_mfma_f32_16x16x32_bf16 v[84:87], v[224:227], v[236:239], v[84:87]
	v_mfma_f32_16x16x32_bf16 v[80:83], v[228:231], v[236:239], v[80:83]
	ds_read_b128 v[236:239], v207 offset:61440
	s_waitcnt lgkmcnt(5)
	v_mfma_f32_16x16x32_bf16 v[76:79], v[212:215], v[240:243], v[76:79]
	ds_read_b128 v[212:215], v145 offset:20480
	v_mfma_f32_16x16x32_bf16 v[72:75], v[220:223], v[240:243], v[72:75]
	ds_read_b128 v[220:223], v145 offset:22528
	v_mfma_f32_16x16x32_bf16 v[68:71], v[224:227], v[240:243], v[68:71]
	ds_read_b128 v[224:227], v145 offset:24576
	v_mfma_f32_16x16x32_bf16 v[64:67], v[228:231], v[240:243], v[64:67]
	s_waitcnt vmcnt(8)
	ds_write_b128 v133, v[28:31]
	s_waitcnt lgkmcnt(7)
	v_mfma_f32_16x16x32_bf16 v[124:127], v[248:251], v[244:247], v[124:127]
	s_waitcnt lgkmcnt(6)
	v_mfma_f32_16x16x32_bf16 v[120:123], v[208:211], v[244:247], v[120:123]
	ds_write_b128 v133, v[36:39] offset:4096
	s_waitcnt lgkmcnt(6)
	v_mfma_f32_16x16x32_bf16 v[116:119], v[232:235], v[244:247], v[116:119]
	s_waitcnt lgkmcnt(5)
	v_mfma_f32_16x16x32_bf16 v[112:115], v[236:239], v[244:247], v[112:115]
	ds_write_b128 v133, v[40:43] offset:8192
	s_waitcnt lgkmcnt(5)
	v_mfma_f32_16x16x32_bf16 v[108:111], v[248:251], v[212:215], v[108:111]
	v_mfma_f32_16x16x32_bf16 v[104:107], v[208:211], v[212:215], v[104:107]
	ds_write_b128 v133, v[44:47] offset:12288
	v_mfma_f32_16x16x32_bf16 v[100:103], v[232:235], v[212:215], v[100:103]
	v_mfma_f32_16x16x32_bf16 v[96:99], v[236:239], v[212:215], v[96:99]
	ds_write_b128 v133, v[48:51] offset:36864
	s_waitcnt lgkmcnt(6)
	v_mfma_f32_16x16x32_bf16 v[92:95], v[248:251], v[220:223], v[92:95]
	v_mfma_f32_16x16x32_bf16 v[88:91], v[208:211], v[220:223], v[88:91]
	ds_write_b128 v133, v[52:55] offset:40960
	v_mfma_f32_16x16x32_bf16 v[84:87], v[232:235], v[220:223], v[84:87]
	v_mfma_f32_16x16x32_bf16 v[80:83], v[236:239], v[220:223], v[80:83]
	ds_write_b128 v133, v[56:59] offset:45056
	s_waitcnt lgkmcnt(7)
	v_mfma_f32_16x16x32_bf16 v[76:79], v[248:251], v[224:227], v[76:79]
	v_mfma_f32_16x16x32_bf16 v[72:75], v[208:211], v[224:227], v[72:75]
	ds_write_b128 v133, v[60:63] offset:49152
	v_mfma_f32_16x16x32_bf16 v[68:71], v[232:235], v[224:227], v[68:71]
	v_mfma_f32_16x16x32_bf16 v[64:67], v[236:239], v[224:227], v[64:67]
	s_setprio 0
	s_cmp_gt_u32 s19, 13
	s_cselect_b64 s[22:23], -1, 0

; template <bool ATRANS = false, bool SWAP = true>
; DEV void gemm_seg(f32x4 (&acc)[4][4], bf16_t* As, bf16_t* Bs, const bf16_t* A, const bf16_t* B, int lda, int ldb,
;                   int K, int arow_lo, int arow_hi) {
;     ...
;   GLOAD(0, 0);
;   GLOAD(1, 1);
;   STAB(0, 0);
;   GLOAD(0, 2);
;   for (int kt = 0; kt < nk; kt += 2) {
;     COMPUTE(kt);
;     STAB(1, kt + 1);
;     GLOAD(1, kt + 3);
;     if (kt + 1 >= nk) break;
;     COMPUTE(kt + 1);
;     STAB(0, kt + 2);
;     GLOAD(0, kt + 4);
.Lvm_win2_ok:
	s_setprio 1
	ds_read_b128 v[208:211], v139 offset:36864
	ds_read_b128 v[212:215], v137
	ds_read_b128 v[220:223], v137 offset:2048
	ds_read_b128 v[224:227], v137 offset:4096
	ds_read_b128 v[228:231], v137 offset:6144
	ds_read_b128 v[232:235], v139 offset:38912
	ds_read_b128 v[236:239], v139 offset:40960
	ds_read_b128 v[240:243], v139 offset:43008
	s_waitcnt lgkmcnt(6)
	v_mfma_f32_16x16x32_bf16 v[124:127], v[212:215], v[208:211], v[124:127]
	ds_read_b128 v[244:247], v207 offset:43008
	ds_read_b128 v[248:251], v145
	s_waitcnt lgkmcnt(7)
	v_mfma_f32_16x16x32_bf16 v[108:111], v[220:223], v[208:211], v[108:111]
	s_waitcnt lgkmcnt(6)
	v_mfma_f32_16x16x32_bf16 v[92:95], v[224:227], v[208:211], v[92:95]
	s_waitcnt lgkmcnt(5)
	v_mfma_f32_16x16x32_bf16 v[76:79], v[228:231], v[208:211], v[76:79]
	ds_read_b128 v[208:211], v145 offset:2048
	s_waitcnt lgkmcnt(5)
	v_mfma_f32_16x16x32_bf16 v[120:123], v[212:215], v[232:235], v[120:123]
	v_mfma_f32_16x16x32_bf16 v[104:107], v[220:223], v[232:235], v[104:107]
	v_mfma_f32_16x16x32_bf16 v[88:91], v[224:227], v[232:235], v[88:91]
	v_mfma_f32_16x16x32_bf16 v[72:75], v[228:231], v[232:235], v[72:75]
	ds_read_b128 v[232:235], v145 offset:4096
	s_waitcnt lgkmcnt(5)
	v_mfma_f32_16x16x32_bf16 v[116:119], v[212:215], v[236:239], v[116:119]
	v_mfma_f32_16x16x32_bf16 v[100:103], v[220:223], v[236:239], v[100:103]
	v_mfma_f32_16x16x32_bf16 v[84:87], v[224:227], v[236:239], v[84:87]
	v_mfma_f32_16x16x32_bf16 v[68:71], v[228:231], v[236:239], v[68:71]
	ds_read_b128 v[236:239], v145 offset:6144
	s_waitcnt lgkmcnt(5)
	v_mfma_f32_16x16x32_bf16 v[112:115], v[212:215], v[240:243], v[112:115]
	ds_read_b128 v[212:215], v207 offset:36864
	v_mfma_f32_16x16x32_bf16 v[96:99], v[220:223], v[240:243], v[96:99]
	ds_read_b128 v[220:223], v207 offset:38912
	v_mfma_f32_16x16x32_bf16 v[80:83], v[224:227], v[240:243], v[80:83]
	ds_read_b128 v[224:227], v207 offset:40960
	v_mfma_f32_16x16x32_bf16 v[64:67], v[228:231], v[240:243], v[64:67]
	s_waitcnt vmcnt(8)
	ds_write_b128 v133, v[0:3] offset:18432
	s_waitcnt lgkmcnt(7)
	v_mfma_f32_16x16x32_bf16 v[112:115], v[248:251], v[244:247], v[112:115]
	s_waitcnt lgkmcnt(6)
	v_mfma_f32_16x16x32_bf16 v[96:99], v[208:211], v[244:247], v[96:99]
	ds_write_b128 v133, v[4:7] offset:22528
	s_waitcnt lgkmcnt(6)
	v_mfma_f32_16x16x32_bf16 v[80:83], v[232:235], v[244:247], v[80:83]
	s_waitcnt lgkmcnt(5)
	v_mfma_f32_16x16x32_bf16 v[64:67], v[236:239], v[244:247], v[64:67]
	ds_write_b128 v133, v[8:11] offset:26624
	s_waitcnt lgkmcnt(5)
	v_mfma_f32_16x16x32_bf16 v[124:127], v[248:251], v[212:215], v[124:127]
	v_mfma_f32_16x16x32_bf16 v[108:111], v[208:211], v[212:215], v[108:111]
	ds_write_b128 v133, v[12:15] offset:30720
	v_mfma_f32_16x16x32_bf16 v[92:95], v[232:235], v[212:215], v[92:95]
	v_mfma_f32_16x16x32_bf16 v[76:79], v[236:239], v[212:215], v[76:79]
	ds_write_b128 v133, v[16:19] offset:55296
	s_waitcnt lgkmcnt(6)
	v_mfma_f32_16x16x32_bf16 v[120:123], v[248:251], v[220:223], v[120:123]
	v_mfma_f32_16x16x32_bf16 v[104:107], v[208:211], v[220:223], v[104:107]
	ds_write_b128 v133, v[20:23] offset:59392
	v_mfma_f32_16x16x32_bf16 v[88:91], v[232:235], v[220:223], v[88:91]
	v_mfma_f32_16x16x32_bf16 v[72:75], v[236:239], v[220:223], v[72:75]
	ds_write_b128 v133, v[24:27] offset:63488
	s_waitcnt lgkmcnt(7)
	v_mfma_f32_16x16x32_bf16 v[116:119], v[248:251], v[224:227], v[116:119]
	v_mfma_f32_16x16x32_bf16 v[100:103], v[208:211], v[224:227], v[100:103]
	ds_write_b128 v135, v[28:31] offset:12288
	v_mfma_f32_16x16x32_bf16 v[84:87], v[232:235], v[224:227], v[84:87]
	v_mfma_f32_16x16x32_bf16 v[68:71], v[236:239], v[224:227], v[68:71]
	s_setprio 0
	s_cmp_gt_u32 s19, 12
	v_lshl_add_u64 v[164:165], v[146:147], 0, v[128:129]
	v_lshl_add_u64 v[162:163], v[148:149], 0, v[128:129]
	v_lshl_add_u64 v[160:161], v[150:151], 0, v[128:129]
	v_lshl_add_u64 v[158:159], v[152:153], 0, v[128:129]
	v_lshl_add_u64 v[156:157], v[154:155], 0, v[128:129]
	s_waitcnt lgkmcnt(0)
	s_barrier
	s_cbranch_scc1 .LBB0_343
	v_add_co_u32_e32 v20, vcc, 0x10000, v156
	global_load_dwordx4 v[0:3], v[164:165], off offset:384
	global_load_dwordx4 v[4:7], v[162:163], off offset:384
	global_load_dwordx4 v[8:11], v[160:161], off offset:384
	global_load_dwordx4 v[12:15], v[158:159], off offset:384
	global_load_dwordx4 v[16:19], v[156:157], off offset:384
	v_addc_co_u32_e32 v21, vcc, 0, v157, vcc
	v_add_co_u32_e32 v24, vcc, 0x20000, v156
	s_nop 1
	v_addc_co_u32_e32 v25, vcc, 0, v157, vcc
	v_add_co_u32_e32 v28, vcc, 0x30000, v156
	global_load_dwordx4 v[20:23], v[20:21], off offset:384
	s_nop 0
	global_load_dwordx4 v[24:27], v[24:25], off offset:384
	v_addc_co_u32_e32 v29, vcc, 0, v157, vcc
	global_load_dwordx4 v[28:31], v[28:29], off offset:384
; template <bool ATRANS = false, bool SWAP = true>
; DEV void gemm_seg(f32x4 (&acc)[4][4], bf16_t* As, bf16_t* Bs, const bf16_t* A, const bf16_t* B, int lda, int ldb,
;                   int K, int arow_lo, int arow_hi) {
;     ...
;   GLOAD(0, 0);
;   GLOAD(1, 1);
;   STAB(0, 0);
;   GLOAD(0, 2);
;   for (int kt = 0; kt < nk; kt += 2) {
;     COMPUTE(kt);
;     STAB(1, kt + 1);
;     GLOAD(1, kt + 3);
;     if (kt + 1 >= nk) break;
;     COMPUTE(kt + 1);
;     STAB(0, kt + 2);
.LBB0_343:
	s_setprio 1
	ds_read_b128 v[208:211], v139 offset:55296
	ds_read_b128 v[212:215], v137 offset:18432
	ds_read_b128 v[220:223], v137 offset:20480
	ds_read_b128 v[224:227], v137 offset:22528
	ds_read_b128 v[228:231], v137 offset:24576
	ds_read_b128 v[232:235], v139 offset:57344
	ds_read_b128 v[236:239], v139 offset:59392
	ds_read_b128 v[240:243], v139 offset:61440
	s_waitcnt lgkmcnt(6)
	v_mfma_f32_16x16x32_bf16 v[124:127], v[212:215], v[208:211], v[124:127]
	ds_read_b128 v[244:247], v207 offset:55296
	ds_read_b128 v[248:251], v145 offset:18432
	s_waitcnt lgkmcnt(7)
	v_mfma_f32_16x16x32_bf16 v[108:111], v[220:223], v[208:211], v[108:111]
	s_waitcnt lgkmcnt(6)
	v_mfma_f32_16x16x32_bf16 v[92:95], v[224:227], v[208:211], v[92:95]
	s_waitcnt lgkmcnt(5)
	v_mfma_f32_16x16x32_bf16 v[76:79], v[228:231], v[208:211], v[76:79]
	ds_read_b128 v[208:211], v145 offset:20480
	s_waitcnt lgkmcnt(5)
	v_mfma_f32_16x16x32_bf16 v[120:123], v[212:215], v[232:235], v[120:123]
	v_mfma_f32_16x16x32_bf16 v[104:107], v[220:223], v[232:235], v[104:107]
	v_mfma_f32_16x16x32_bf16 v[88:91], v[224:227], v[232:235], v[88:91]
	v_mfma_f32_16x16x32_bf16 v[72:75], v[228:231], v[232:235], v[72:75]
	ds_read_b128 v[232:235], v145 offset:22528
	s_waitcnt lgkmcnt(5)
	v_mfma_f32_16x16x32_bf16 v[116:119], v[212:215], v[236:239], v[116:119]
	v_mfma_f32_16x16x32_bf16 v[100:103], v[220:223], v[236:239], v[100:103]
	v_mfma_f32_16x16x32_bf16 v[84:87], v[224:227], v[236:239], v[84:87]
	v_mfma_f32_16x16x32_bf16 v[68:71], v[228:231], v[236:239], v[68:71]
	ds_read_b128 v[236:239], v145 offset:24576
	s_waitcnt lgkmcnt(5)
	v_mfma_f32_16x16x32_bf16 v[112:115], v[212:215], v[240:243], v[112:115]
	ds_read_b128 v[212:215], v207 offset:57344
	v_mfma_f32_16x16x32_bf16 v[96:99], v[220:223], v[240:243], v[96:99]
	ds_read_b128 v[220:223], v207 offset:59392
	v_mfma_f32_16x16x32_bf16 v[80:83], v[224:227], v[240:243], v[80:83]
	ds_read_b128 v[224:227], v207 offset:61440
	v_mfma_f32_16x16x32_bf16 v[64:67], v[228:231], v[240:243], v[64:67]
	s_waitcnt vmcnt(8)
	ds_write_b128 v133, v[32:35]
	s_waitcnt lgkmcnt(7)
	v_mfma_f32_16x16x32_bf16 v[124:127], v[248:251], v[244:247], v[124:127]
	s_waitcnt lgkmcnt(6)
	v_mfma_f32_16x16x32_bf16 v[108:111], v[208:211], v[244:247], v[108:111]
	ds_write_b128 v133, v[36:39] offset:4096
	s_waitcnt lgkmcnt(6)
	v_mfma_f32_16x16x32_bf16 v[92:95], v[232:235], v[244:247], v[92:95]
	s_waitcnt lgkmcnt(5)
	v_mfma_f32_16x16x32_bf16 v[76:79], v[236:239], v[244:247], v[76:79]
	ds_write_b128 v133, v[40:43] offset:8192
	s_waitcnt lgkmcnt(5)
	v_mfma_f32_16x16x32_bf16 v[120:123], v[248:251], v[212:215], v[120:123]
	v_mfma_f32_16x16x32_bf16 v[104:107], v[208:211], v[212:215], v[104:107]
	ds_write_b128 v133, v[44:47] offset:12288
	v_mfma_f32_16x16x32_bf16 v[88:91], v[232:235], v[212:215], v[88:91]
	v_mfma_f32_16x16x32_bf16 v[72:75], v[236:239], v[212:215], v[72:75]
	ds_write_b128 v133, v[48:51] offset:36864
	s_waitcnt lgkmcnt(6)
	v_mfma_f32_16x16x32_bf16 v[116:119], v[248:251], v[220:223], v[116:119]
	v_mfma_f32_16x16x32_bf16 v[100:103], v[208:211], v[220:223], v[100:103]
	ds_write_b128 v133, v[52:55] offset:40960
	v_mfma_f32_16x16x32_bf16 v[84:87], v[232:235], v[220:223], v[84:87]
	v_mfma_f32_16x16x32_bf16 v[68:71], v[236:239], v[220:223], v[68:71]
	ds_write_b128 v133, v[56:59] offset:45056
	s_waitcnt lgkmcnt(7)
	v_mfma_f32_16x16x32_bf16 v[112:115], v[248:251], v[224:227], v[112:115]
	v_mfma_f32_16x16x32_bf16 v[96:99], v[208:211], v[224:227], v[96:99]
	ds_write_b128 v133, v[60:63] offset:49152
	v_mfma_f32_16x16x32_bf16 v[80:83], v[232:235], v[224:227], v[80:83]
	v_mfma_f32_16x16x32_bf16 v[64:67], v[236:239], v[224:227], v[64:67]
	s_setprio 0
	s_cmp_gt_u32 s19, 13
	s_cselect_b64 s[0:1], -1, 0

; template <bool ATRANS = false, bool SWAP = true>
; DEV void gemm_seg(f32x4 (&acc)[4][4], bf16_t* As, bf16_t* Bs, const bf16_t* A, const bf16_t* B, int lda, int ldb,
;                   int K, int arow_lo, int arow_hi) {
;     ...
;   GLOAD(0, 0);
;   GLOAD(1, 1);
;   STAB(0, 0);
;   GLOAD(0, 2);
;   for (int kt = 0; kt < nk; kt += 2) {
;     COMPUTE(kt);
;     STAB(1, kt + 1);
;     GLOAD(1, kt + 3);
;     if (kt + 1 >= nk) break;
;     COMPUTE(kt + 1);
;     STAB(0, kt + 2);
;     GLOAD(0, kt + 4);
.Lvm_up_ok:
	s_setprio 1
	ds_read_b128 v[168:171], v139
	ds_read_b128 v[208:211], v164 offset:36864
	ds_read_b128 v[212:215], v164 offset:38912
	ds_read_b128 v[220:223], v164 offset:40960
	ds_read_b128 v[224:227], v164 offset:43008
	ds_read_b128 v[228:231], v139 offset:2048
	ds_read_b128 v[232:235], v139 offset:4096
	ds_read_b128 v[236:239], v139 offset:6144
	s_waitcnt lgkmcnt(6)
	v_mfma_f32_16x16x32_bf16 v[124:127], v[208:211], v[168:171], v[124:127]
	ds_read_b128 v[240:243], v165
	ds_read_b128 v[244:247], v207 offset:36864
	s_waitcnt lgkmcnt(7)
	v_mfma_f32_16x16x32_bf16 v[120:123], v[212:215], v[168:171], v[120:123]
	s_waitcnt lgkmcnt(6)
	v_mfma_f32_16x16x32_bf16 v[116:119], v[220:223], v[168:171], v[116:119]
	s_waitcnt lgkmcnt(5)
	v_mfma_f32_16x16x32_bf16 v[112:115], v[224:227], v[168:171], v[112:115]
	ds_read_b128 v[168:171], v207 offset:38912
	s_waitcnt lgkmcnt(5)
	v_mfma_f32_16x16x32_bf16 v[108:111], v[208:211], v[228:231], v[108:111]
	v_mfma_f32_16x16x32_bf16 v[104:107], v[212:215], v[228:231], v[104:107]
	v_mfma_f32_16x16x32_bf16 v[100:103], v[220:223], v[228:231], v[100:103]
	v_mfma_f32_16x16x32_bf16 v[96:99], v[224:227], v[228:231], v[96:99]
	ds_read_b128 v[228:231], v207 offset:40960
	s_waitcnt lgkmcnt(5)
	v_mfma_f32_16x16x32_bf16 v[92:95], v[208:211], v[232:235], v[92:95]
	v_mfma_f32_16x16x32_bf16 v[88:91], v[212:215], v[232:235], v[88:91]
	v_mfma_f32_16x16x32_bf16 v[84:87], v[220:223], v[232:235], v[84:87]
	v_mfma_f32_16x16x32_bf16 v[80:83], v[224:227], v[232:235], v[80:83]
	ds_read_b128 v[232:235], v207 offset:43008
	s_waitcnt lgkmcnt(5)
	v_mfma_f32_16x16x32_bf16 v[76:79], v[208:211], v[236:239], v[76:79]
	ds_read_b128 v[208:211], v165 offset:2048
	v_mfma_f32_16x16x32_bf16 v[72:75], v[212:215], v[236:239], v[72:75]
	ds_read_b128 v[212:215], v165 offset:4096
	v_mfma_f32_16x16x32_bf16 v[68:71], v[220:223], v[236:239], v[68:71]
	ds_read_b128 v[220:223], v165 offset:6144
	v_mfma_f32_16x16x32_bf16 v[64:67], v[224:227], v[236:239], v[64:67]
	s_waitcnt vmcnt(8)
	ds_write_b128 v135, v[0:3] offset:18432
	s_waitcnt lgkmcnt(7)
	v_mfma_f32_16x16x32_bf16 v[124:127], v[244:247], v[240:243], v[124:127]
	s_waitcnt lgkmcnt(6)
	v_mfma_f32_16x16x32_bf16 v[120:123], v[168:171], v[240:243], v[120:123]
	ds_write_b128 v135, v[4:7] offset:22528
	s_waitcnt lgkmcnt(6)
	v_mfma_f32_16x16x32_bf16 v[116:119], v[228:231], v[240:243], v[116:119]
	s_waitcnt lgkmcnt(5)
	v_mfma_f32_16x16x32_bf16 v[112:115], v[232:235], v[240:243], v[112:115]
	ds_write_b128 v135, v[8:11] offset:26624
	s_waitcnt lgkmcnt(5)
	v_mfma_f32_16x16x32_bf16 v[108:111], v[244:247], v[208:211], v[108:111]
	v_mfma_f32_16x16x32_bf16 v[104:107], v[168:171], v[208:211], v[104:107]
	ds_write_b128 v135, v[12:15] offset:30720
	v_mfma_f32_16x16x32_bf16 v[100:103], v[228:231], v[208:211], v[100:103]
	v_mfma_f32_16x16x32_bf16 v[96:99], v[232:235], v[208:211], v[96:99]
	ds_write_b128 v135, v[16:19] offset:55296
	s_waitcnt lgkmcnt(6)
	v_mfma_f32_16x16x32_bf16 v[92:95], v[244:247], v[212:215], v[92:95]
	v_mfma_f32_16x16x32_bf16 v[88:91], v[168:171], v[212:215], v[88:91]
	ds_write_b128 v135, v[20:23] offset:59392
	v_mfma_f32_16x16x32_bf16 v[84:87], v[228:231], v[212:215], v[84:87]
	v_mfma_f32_16x16x32_bf16 v[80:83], v[232:235], v[212:215], v[80:83]
	ds_write_b128 v135, v[24:27] offset:63488
	s_waitcnt lgkmcnt(7)
	v_mfma_f32_16x16x32_bf16 v[76:79], v[244:247], v[220:223], v[76:79]
	v_mfma_f32_16x16x32_bf16 v[72:75], v[168:171], v[220:223], v[72:75]
	ds_write_b128 v137, v[32:35] offset:12288
	v_mfma_f32_16x16x32_bf16 v[68:71], v[228:231], v[220:223], v[68:71]
	v_mfma_f32_16x16x32_bf16 v[64:67], v[232:235], v[220:223], v[64:67]
	s_setprio 0
	s_cmp_gt_u32 s22, 12
	v_lshl_add_u64 v[162:163], v[146:147], 0, v[128:129]
	v_lshl_add_u64 v[160:161], v[148:149], 0, v[128:129]
	v_lshl_add_u64 v[158:159], v[150:151], 0, v[128:129]
	v_lshl_add_u64 v[156:157], v[152:153], 0, v[128:129]
	v_lshl_add_u64 v[154:155], v[144:145], 0, v[128:129]
	s_waitcnt lgkmcnt(0)
	s_barrier
	s_cbranch_scc1 .LBB0_826
	v_add_co_u32_e32 v20, vcc, 0x10000, v154
	global_load_dwordx4 v[0:3], v[162:163], off
	global_load_dwordx4 v[4:7], v[160:161], off
	global_load_dwordx4 v[8:11], v[158:159], off
	global_load_dwordx4 v[12:15], v[156:157], off
	global_load_dwordx4 v[16:19], v[154:155], off offset:384
	v_addc_co_u32_e32 v21, vcc, 0, v155, vcc
	v_add_co_u32_e32 v24, vcc, 0x20000, v154
	s_nop 1
	v_addc_co_u32_e32 v25, vcc, 0, v155, vcc
	v_add_co_u32_e32 v32, vcc, 0x30000, v154
	global_load_dwordx4 v[20:23], v[20:21], off offset:384
	s_nop 0
	global_load_dwordx4 v[24:27], v[24:25], off offset:384
	v_addc_co_u32_e32 v33, vcc, 0, v155, vcc
	global_load_dwordx4 v[32:35], v[32:33], off offset:384
; template <bool ATRANS = false, bool SWAP = true>
; DEV void gemm_seg(f32x4 (&acc)[4][4], bf16_t* As, bf16_t* Bs, const bf16_t* A, const bf16_t* B, int lda, int ldb,
;                   int K, int arow_lo, int arow_hi) {
;     ...
;   GLOAD(0, 0);
;   GLOAD(1, 1);
;   STAB(0, 0);
;   GLOAD(0, 2);
;   for (int kt = 0; kt < nk; kt += 2) {
;     COMPUTE(kt);
;     STAB(1, kt + 1);
;     GLOAD(1, kt + 3);
;     if (kt + 1 >= nk) break;
;     COMPUTE(kt + 1);
;     STAB(0, kt + 2);
.LBB0_826:
	s_setprio 1
	ds_read_b128 v[168:171], v139 offset:18432
	ds_read_b128 v[208:211], v164 offset:55296
	ds_read_b128 v[212:215], v164 offset:57344
	ds_read_b128 v[220:223], v164 offset:59392
	ds_read_b128 v[224:227], v164 offset:61440
	ds_read_b128 v[228:231], v139 offset:20480
	ds_read_b128 v[232:235], v139 offset:22528
	ds_read_b128 v[236:239], v139 offset:24576
	s_waitcnt lgkmcnt(6)
	v_mfma_f32_16x16x32_bf16 v[124:127], v[208:211], v[168:171], v[124:127]
	ds_read_b128 v[240:243], v165 offset:18432
	ds_read_b128 v[244:247], v207 offset:55296
	s_waitcnt lgkmcnt(7)
	v_mfma_f32_16x16x32_bf16 v[120:123], v[212:215], v[168:171], v[120:123]
	s_waitcnt lgkmcnt(6)
	v_mfma_f32_16x16x32_bf16 v[116:119], v[220:223], v[168:171], v[116:119]
	s_waitcnt lgkmcnt(5)
	v_mfma_f32_16x16x32_bf16 v[112:115], v[224:227], v[168:171], v[112:115]
	ds_read_b128 v[168:171], v207 offset:57344
	s_waitcnt lgkmcnt(5)
	v_mfma_f32_16x16x32_bf16 v[108:111], v[208:211], v[228:231], v[108:111]
	v_mfma_f32_16x16x32_bf16 v[104:107], v[212:215], v[228:231], v[104:107]
	v_mfma_f32_16x16x32_bf16 v[100:103], v[220:223], v[228:231], v[100:103]
	v_mfma_f32_16x16x32_bf16 v[96:99], v[224:227], v[228:231], v[96:99]
	ds_read_b128 v[228:231], v207 offset:59392
	s_waitcnt lgkmcnt(5)
	v_mfma_f32_16x16x32_bf16 v[92:95], v[208:211], v[232:235], v[92:95]
	v_mfma_f32_16x16x32_bf16 v[88:91], v[212:215], v[232:235], v[88:91]
	v_mfma_f32_16x16x32_bf16 v[84:87], v[220:223], v[232:235], v[84:87]
	v_mfma_f32_16x16x32_bf16 v[80:83], v[224:227], v[232:235], v[80:83]
	ds_read_b128 v[232:235], v207 offset:61440
	s_waitcnt lgkmcnt(5)
	v_mfma_f32_16x16x32_bf16 v[76:79], v[208:211], v[236:239], v[76:79]
	ds_read_b128 v[208:211], v165 offset:20480
	v_mfma_f32_16x16x32_bf16 v[72:75], v[212:215], v[236:239], v[72:75]
	ds_read_b128 v[212:215], v165 offset:22528
	v_mfma_f32_16x16x32_bf16 v[68:71], v[220:223], v[236:239], v[68:71]
	ds_read_b128 v[220:223], v165 offset:24576
	v_mfma_f32_16x16x32_bf16 v[64:67], v[224:227], v[236:239], v[64:67]
	s_waitcnt vmcnt(8)
	ds_write_b128 v135, v[28:31]
	s_waitcnt lgkmcnt(7)
	v_mfma_f32_16x16x32_bf16 v[124:127], v[244:247], v[240:243], v[124:127]
	s_waitcnt lgkmcnt(6)
	v_mfma_f32_16x16x32_bf16 v[120:123], v[168:171], v[240:243], v[120:123]
	ds_write_b128 v135, v[36:39] offset:4096
	s_waitcnt lgkmcnt(6)
	v_mfma_f32_16x16x32_bf16 v[116:119], v[228:231], v[240:243], v[116:119]
	s_waitcnt lgkmcnt(5)
	v_mfma_f32_16x16x32_bf16 v[112:115], v[232:235], v[240:243], v[112:115]
	ds_write_b128 v135, v[40:43] offset:8192
	s_waitcnt lgkmcnt(5)
	v_mfma_f32_16x16x32_bf16 v[108:111], v[244:247], v[208:211], v[108:111]
	v_mfma_f32_16x16x32_bf16 v[104:107], v[168:171], v[208:211], v[104:107]
	ds_write_b128 v135, v[44:47] offset:12288
	v_mfma_f32_16x16x32_bf16 v[100:103], v[228:231], v[208:211], v[100:103]
	v_mfma_f32_16x16x32_bf16 v[96:99], v[232:235], v[208:211], v[96:99]
	ds_write_b128 v135, v[48:51] offset:36864
	s_waitcnt lgkmcnt(6)
	v_mfma_f32_16x16x32_bf16 v[92:95], v[244:247], v[212:215], v[92:95]
	v_mfma_f32_16x16x32_bf16 v[88:91], v[168:171], v[212:215], v[88:91]
	ds_write_b128 v135, v[52:55] offset:40960
	v_mfma_f32_16x16x32_bf16 v[84:87], v[228:231], v[212:215], v[84:87]
	v_mfma_f32_16x16x32_bf16 v[80:83], v[232:235], v[212:215], v[80:83]
	ds_write_b128 v135, v[56:59] offset:45056
	s_waitcnt lgkmcnt(7)
	v_mfma_f32_16x16x32_bf16 v[76:79], v[244:247], v[220:223], v[76:79]
	v_mfma_f32_16x16x32_bf16 v[72:75], v[168:171], v[220:223], v[72:75]
	ds_write_b128 v135, v[60:63] offset:49152
	v_mfma_f32_16x16x32_bf16 v[68:71], v[228:231], v[220:223], v[68:71]
	v_mfma_f32_16x16x32_bf16 v[64:67], v[232:235], v[220:223], v[64:67]
	s_setprio 0
	s_cmp_gt_u32 s22, 13
	s_cselect_b64 s[0:1], -1, 0

; DEV int TID() { int t = threadIdx.x; asm volatile("" : "+v"(t)); return t; }
; template <bool ATRANS = false, bool SWAP = true>
; DEV void gemm_seg(f32x4 (&acc)[4][4], bf16_t* As, bf16_t* Bs, const bf16_t* A, const bf16_t* B, int lda, int ldb,
;                   int K, int arow_lo, int arow_hi) {
;     ...
;   const bool av0 = (lrow >= arow_lo) && (lrow < arow_hi), av1 = (lrow + 32 >= arow_lo) && (lrow + 32 < arow_hi),
;              av2 = (lrow + 64 >= arow_lo) && (lrow + 64 < arow_hi), av3 = (lrow + 96 >= arow_lo) && (lrow + 96 < arow_hi);
;   const int c0 = min(max(lrow, arow_lo), arow_hi - 1), c1 = min(max(lrow + 32, arow_lo), arow_hi - 1),
;             c2 = min(max(lrow + 64, arow_lo), arow_hi - 1), c3 = min(max(lrow + 96, arow_lo), arow_hi - 1);
;   const bf16_t* a0 = ATRANS ? A + (long)(tk) * lda + trg : A + (long)c0 * lda + lk;
;   const bf16_t* a1 = ATRANS ? A + (long)(tk + 16) * lda + trg : A + (long)c1 * lda + lk;
;   const bf16_t* a2 = ATRANS ? A + (long)(tk + 32) * lda + trg : A + (long)c2 * lda + lk;
;   const bf16_t* a3 = ATRANS ? A + (long)(tk + 48) * lda + trg : A + (long)c3 * lda + lk;
;   const bf16_t* b0 = B + (long)lrow * ldb + lk;
;   const long bstep = 32L * ldb;
;   const long astep = ATRANS ? (long)lda : 1L;
;   uint4 A0a, A0b, A0c, A0d, B0a, B0b, B0c, B0d;
;   uint4 A1a, A1b, A1c, A1d, B1a, B1b, B1c, B1d;
;   const int so = lrow * LDT + lk;
;   const int sw = lrow * 64 + (((lk >> 3) ^ (lrow & 7)) * 8);
;   const int nk = K / BK;
;   const unsigned am0 = av0 ? 0xffffffffu : 0u, am1 = av1 ? 0xffffffffu : 0u, am2 = av2 ? 0xffffffffu : 0u,
;                  am3 = av3 ? 0xffffffffu : 0u;
; DEV void acc_to_lds(float* Cs, f32x4 (&acc)[4][4]) {
;   const int lane = TID() & 63, wid = TID() >> 6, wr = wid >> 1, wc = wid & 1;
;   const int fr = lane & 15, fq = lane >> 4;
; #pragma unroll
;   for (int m = 0; m < 4; ++m)
; #pragma unroll
;     for (int n = 0; n < 4; ++n)
;       *(f32x4*)(Cs + (wr * 64 + m * 16 + fr) * CS_LD + wc * 64 + n * 16 + fq * 4) = acc[m][n];
;   __syncthreads();
.LBB0_830:
	s_sub_i32 s0, 1, s34
	s_max_i32 s0, s0, 0
	s_sub_i32 s1, 0x1001, s34
	s_min_u32 s1, s1, 0x80
	v_and_b32_e32 v168, 15, v166
	v_lshrrev_b32_e32 v169, 7, v166
	v_lshl_add_u32 v168, v169, 6, v168
	v_add_u32_e32 v169, 0, v168
	v_cmp_le_i32_e32 vcc, s0, v169
	v_cmp_gt_i32_e64 s[2:3], s1, v169
	s_and_b64 vcc, vcc, s[2:3]
	v_cndmask_b32_e32 v112, 0, v112, vcc
	v_cndmask_b32_e32 v113, 0, v113, vcc
	v_cndmask_b32_e32 v114, 0, v114, vcc
	v_cndmask_b32_e32 v115, 0, v115, vcc
	v_cndmask_b32_e32 v116, 0, v116, vcc
	v_cndmask_b32_e32 v117, 0, v117, vcc
	v_cndmask_b32_e32 v118, 0, v118, vcc
	v_cndmask_b32_e32 v119, 0, v119, vcc
	v_cndmask_b32_e32 v120, 0, v120, vcc
	v_cndmask_b32_e32 v121, 0, v121, vcc
	v_cndmask_b32_e32 v122, 0, v122, vcc
	v_cndmask_b32_e32 v123, 0, v123, vcc
	v_cndmask_b32_e32 v124, 0, v124, vcc
	v_cndmask_b32_e32 v125, 0, v125, vcc
	v_cndmask_b32_e32 v126, 0, v126, vcc
	v_cndmask_b32_e32 v127, 0, v127, vcc
	v_add_u32_e32 v169, 16, v168
	v_cmp_le_i32_e32 vcc, s0, v169
	v_cmp_gt_i32_e64 s[2:3], s1, v169
	s_and_b64 vcc, vcc, s[2:3]
	v_cndmask_b32_e32 v96, 0, v96, vcc
	v_cndmask_b32_e32 v97, 0, v97, vcc
	v_cndmask_b32_e32 v98, 0, v98, vcc
	v_cndmask_b32_e32 v99, 0, v99, vcc
	v_cndmask_b32_e32 v100, 0, v100, vcc
	v_cndmask_b32_e32 v101, 0, v101, vcc
	v_cndmask_b32_e32 v102, 0, v102, vcc
	v_cndmask_b32_e32 v103, 0, v103, vcc
	v_cndmask_b32_e32 v104, 0, v104, vcc
	v_cndmask_b32_e32 v105, 0, v105, vcc
	v_cndmask_b32_e32 v106, 0, v106, vcc
	v_cndmask_b32_e32 v107, 0, v107, vcc
	v_cndmask_b32_e32 v108, 0, v108, vcc
	v_cndmask_b32_e32 v109, 0, v109, vcc
	v_cndmask_b32_e32 v110, 0, v110, vcc
	v_cndmask_b32_e32 v111, 0, v111, vcc
	v_add_u32_e32 v169, 32, v168
	v_cmp_le_i32_e32 vcc, s0, v169
	v_cmp_gt_i32_e64 s[2:3], s1, v169
	s_and_b64 vcc, vcc, s[2:3]
	v_cndmask_b32_e32 v80, 0, v80, vcc
	v_cndmask_b32_e32 v81, 0, v81, vcc
	v_cndmask_b32_e32 v82, 0, v82, vcc
	v_cndmask_b32_e32 v83, 0, v83, vcc
	v_cndmask_b32_e32 v84, 0, v84, vcc
	v_cndmask_b32_e32 v85, 0, v85, vcc
	v_cndmask_b32_e32 v86, 0, v86, vcc
	v_cndmask_b32_e32 v87, 0, v87, vcc
	v_cndmask_b32_e32 v88, 0, v88, vcc
	v_cndmask_b32_e32 v89, 0, v89, vcc
	v_cndmask_b32_e32 v90, 0, v90, vcc
	v_cndmask_b32_e32 v91, 0, v91, vcc
	v_cndmask_b32_e32 v92, 0, v92, vcc
	v_cndmask_b32_e32 v93, 0, v93, vcc
	v_cndmask_b32_e32 v94, 0, v94, vcc
	v_cndmask_b32_e32 v95, 0, v95, vcc
	v_add_u32_e32 v169, 48, v168
	v_cmp_le_i32_e32 vcc, s0, v169
	v_cmp_gt_i32_e64 s[2:3], s1, v169
	s_and_b64 vcc, vcc, s[2:3]
	v_cndmask_b32_e32 v64, 0, v64, vcc
	v_cndmask_b32_e32 v65, 0, v65, vcc
	v_cndmask_b32_e32 v66, 0, v66, vcc
	v_cndmask_b32_e32 v67, 0, v67, vcc
	v_cndmask_b32_e32 v68, 0, v68, vcc
	v_cndmask_b32_e32 v69, 0, v69, vcc
	v_cndmask_b32_e32 v70, 0, v70, vcc
	v_cndmask_b32_e32 v71, 0, v71, vcc
	v_cndmask_b32_e32 v72, 0, v72, vcc
	v_cndmask_b32_e32 v73, 0, v73, vcc
	v_cndmask_b32_e32 v74, 0, v74, vcc
	v_cndmask_b32_e32 v75, 0, v75, vcc
	v_cndmask_b32_e32 v76, 0, v76, vcc
	v_cndmask_b32_e32 v77, 0, v77, vcc
	v_cndmask_b32_e32 v78, 0, v78, vcc
	v_cndmask_b32_e32 v79, 0, v79, vcc
	s_waitcnt vmcnt(7)
	v_mov_b32_e32 v0, v166
	v_mov_b32_e32 v1, v166
	s_mov_b32 s0, 0xfffffc0
	v_and_b32_e32 v2, 64, v1
	v_and_b32_e32 v3, 15, v0
	v_lshrrev_b32_e32 v1, 1, v1
	v_and_b32_e32 v0, 48, v0
	v_and_or_b32 v1, v1, s0, v3
	v_lshl_or_b32 v0, v2, 2, v0
	v_mad_u64_u32 v[0:1], s[0:1], v1, s88, v[0:1]
	s_movk_i32 s0, 0x80
	s_nop 0
	v_cmp_gt_i32_e32 vcc, s0, v133
	ds_write_b128 v0, v[124:127]
	ds_write_b128 v0, v[120:123] offset:64
	ds_write_b128 v0, v[116:119] offset:128
	ds_write_b128 v0, v[112:115] offset:192
	ds_write_b128 v0, v[108:111] offset:8448
	ds_write_b128 v0, v[104:107] offset:8512
	ds_write_b128 v0, v[100:103] offset:8576
	ds_write_b128 v0, v[96:99] offset:8640
	ds_write_b128 v0, v[92:95] offset:16896
	ds_write_b128 v0, v[88:91] offset:16960
	ds_write_b128 v0, v[84:87] offset:17024
	ds_write_b128 v0, v[80:83] offset:17088
	ds_write_b128 v0, v[76:79] offset:25344
	ds_write_b128 v0, v[72:75] offset:25408
	ds_write_b128 v0, v[68:71] offset:25472
	ds_write_b128 v0, v[64:67] offset:25536
	s_waitcnt lgkmcnt(0)
	s_barrier
	s_and_saveexec_b64 s[0:1], vcc
	s_cbranch_execz .LBB0_832
	s_waitcnt vmcnt(5)
	v_add_u32_e32 v8, s21, v133
	v_med3_i32 v0, v8, 0, v206
	v_or_b32_e32 v0, s18, v0
	v_mov_b32_e32 v1, s19
	v_lshlrev_b64 v[0:1], 5, v[0:1]
	v_lshl_add_u64 v[4:5], s[24:25], 0, v[0:1]
	global_load_dwordx4 v[0:3], v[4:5], off
	s_nop 0
	global_load_dwordx4 v[4:7], v[4:5], off offset:16
	s_waitcnt vmcnt(1)
	v_add_f32_e32 v0, v0, v1
	v_add_f32_e32 v0, v0, v2
	v_add_f32_e32 v0, v0, v3
	s_waitcnt vmcnt(0)
	v_add_f32_e32 v0, v0, v4
	v_add_f32_e32 v0, v0, v5
	v_add_f32_e32 v0, v0, v6
	v_add_f32_e32 v0, v0, v7
	v_fmamk_f32 v0, v0, 0x3a800000, v175
	v_mul_f32_e32 v1, 0x4b800000, v0
	v_cmp_gt_f32_e32 vcc, s91, v0
	s_nop 1
	v_cndmask_b32_e32 v0, v0, v1, vcc
	v_rsq_f32_e32 v0, v0
	s_nop 0
	v_mul_f32_e32 v1, 0x45800000, v0
	v_cndmask_b32_e32 v0, v0, v1, vcc
	v_cmp_gt_u32_e32 vcc, s33, v8
	v_mul_lo_u32 v1, v133, s88
	s_nop 0
	v_cndmask_b32_e32 v0, 0, v0, vcc
	ds_write_b32 v1, v0 offset:512

; template <bool ATRANS = false, bool SWAP = true>
; DEV void gemm_seg(f32x4 (&acc)[4][4], bf16_t* As, bf16_t* Bs, const bf16_t* A, const bf16_t* B, int lda, int ldb,
;                   int K, int arow_lo, int arow_hi) {
;     ...
;   GLOAD(0, 0);
;   GLOAD(1, 1);
;   STAB(0, 0);
;   GLOAD(0, 2);
;   for (int kt = 0; kt < nk; kt += 2) {
;     COMPUTE(kt);
;     STAB(1, kt + 1);
;     GLOAD(1, kt + 3);
;     if (kt + 1 >= nk) break;
;     COMPUTE(kt + 1);
;     STAB(0, kt + 2);
;     GLOAD(0, kt + 4);
.Lvm_down_ok:
	s_setprio 1
	ds_read_b128 v[168:171], v137
	ds_read_b128 v[208:211], v139 offset:36864
	ds_read_b128 v[212:215], v139 offset:38912
	ds_read_b128 v[220:223], v139 offset:40960
	ds_read_b128 v[224:227], v139 offset:43008
	ds_read_b128 v[228:231], v137 offset:2048
	ds_read_b128 v[232:235], v137 offset:4096
	ds_read_b128 v[236:239], v137 offset:6144
	s_waitcnt lgkmcnt(6)
	v_mfma_f32_16x16x32_bf16 v[124:127], v[208:211], v[168:171], v[124:127]
	ds_read_b128 v[240:243], v164
	ds_read_b128 v[244:247], v165 offset:36864
	s_waitcnt lgkmcnt(7)
	v_mfma_f32_16x16x32_bf16 v[120:123], v[212:215], v[168:171], v[120:123]
	s_waitcnt lgkmcnt(6)
	v_mfma_f32_16x16x32_bf16 v[116:119], v[220:223], v[168:171], v[116:119]
	s_waitcnt lgkmcnt(5)
	v_mfma_f32_16x16x32_bf16 v[112:115], v[224:227], v[168:171], v[112:115]
	ds_read_b128 v[168:171], v165 offset:38912
	s_waitcnt lgkmcnt(5)
	v_mfma_f32_16x16x32_bf16 v[108:111], v[208:211], v[228:231], v[108:111]
	v_mfma_f32_16x16x32_bf16 v[104:107], v[212:215], v[228:231], v[104:107]
	v_mfma_f32_16x16x32_bf16 v[100:103], v[220:223], v[228:231], v[100:103]
	v_mfma_f32_16x16x32_bf16 v[96:99], v[224:227], v[228:231], v[96:99]
	ds_read_b128 v[228:231], v165 offset:40960
	s_waitcnt lgkmcnt(5)
	v_mfma_f32_16x16x32_bf16 v[92:95], v[208:211], v[232:235], v[92:95]
	v_mfma_f32_16x16x32_bf16 v[88:91], v[212:215], v[232:235], v[88:91]
	v_mfma_f32_16x16x32_bf16 v[84:87], v[220:223], v[232:235], v[84:87]
	v_mfma_f32_16x16x32_bf16 v[80:83], v[224:227], v[232:235], v[80:83]
	ds_read_b128 v[232:235], v165 offset:43008
	s_waitcnt lgkmcnt(5)
	v_mfma_f32_16x16x32_bf16 v[76:79], v[208:211], v[236:239], v[76:79]
	ds_read_b128 v[208:211], v164 offset:2048
	v_mfma_f32_16x16x32_bf16 v[72:75], v[212:215], v[236:239], v[72:75]
	ds_read_b128 v[212:215], v164 offset:4096
	v_mfma_f32_16x16x32_bf16 v[68:71], v[220:223], v[236:239], v[68:71]
	ds_read_b128 v[220:223], v164 offset:6144
	v_mfma_f32_16x16x32_bf16 v[64:67], v[224:227], v[236:239], v[64:67]
	s_waitcnt vmcnt(8)
	ds_write_b128 v133, v[0:3] offset:18432
	s_waitcnt lgkmcnt(7)
	v_mfma_f32_16x16x32_bf16 v[124:127], v[244:247], v[240:243], v[124:127]
	s_waitcnt lgkmcnt(6)
	v_mfma_f32_16x16x32_bf16 v[120:123], v[168:171], v[240:243], v[120:123]
	ds_write_b128 v133, v[4:7] offset:22528
	s_waitcnt lgkmcnt(6)
	v_mfma_f32_16x16x32_bf16 v[116:119], v[228:231], v[240:243], v[116:119]
	s_waitcnt lgkmcnt(5)
	v_mfma_f32_16x16x32_bf16 v[112:115], v[232:235], v[240:243], v[112:115]
	ds_write_b128 v133, v[8:11] offset:26624
	s_waitcnt lgkmcnt(5)
	v_mfma_f32_16x16x32_bf16 v[108:111], v[244:247], v[208:211], v[108:111]
	v_mfma_f32_16x16x32_bf16 v[104:107], v[168:171], v[208:211], v[104:107]
	ds_write_b128 v133, v[12:15] offset:30720
	v_mfma_f32_16x16x32_bf16 v[100:103], v[228:231], v[208:211], v[100:103]
	v_mfma_f32_16x16x32_bf16 v[96:99], v[232:235], v[208:211], v[96:99]
	ds_write_b128 v133, v[16:19] offset:55296
	s_waitcnt lgkmcnt(6)
	v_mfma_f32_16x16x32_bf16 v[92:95], v[244:247], v[212:215], v[92:95]
	v_mfma_f32_16x16x32_bf16 v[88:91], v[168:171], v[212:215], v[88:91]
	ds_write_b128 v133, v[20:23] offset:59392
	v_mfma_f32_16x16x32_bf16 v[84:87], v[228:231], v[212:215], v[84:87]
	v_mfma_f32_16x16x32_bf16 v[80:83], v[232:235], v[212:215], v[80:83]
	ds_write_b128 v133, v[24:27] offset:63488
	s_waitcnt lgkmcnt(7)
	v_mfma_f32_16x16x32_bf16 v[76:79], v[244:247], v[220:223], v[76:79]
	v_mfma_f32_16x16x32_bf16 v[72:75], v[168:171], v[220:223], v[72:75]
	ds_write_b128 v135, v[32:35] offset:12288
	v_mfma_f32_16x16x32_bf16 v[68:71], v[228:231], v[220:223], v[68:71]
	v_mfma_f32_16x16x32_bf16 v[64:67], v[232:235], v[220:223], v[64:67]
	s_setprio 0
	s_cmp_gt_u32 s24, 40
	v_lshl_add_u64 v[162:163], v[144:145], 0, v[128:129]
	v_lshl_add_u64 v[160:161], v[146:147], 0, v[128:129]
	v_lshl_add_u64 v[158:159], v[148:149], 0, v[128:129]
	v_lshl_add_u64 v[156:157], v[150:151], 0, v[128:129]
	v_lshl_add_u64 v[154:155], v[152:153], 0, v[128:129]
	s_waitcnt lgkmcnt(0)
	s_barrier
	s_cbranch_scc1 .LBB0_876
	v_add_co_u32_e32 v20, vcc, 0x2c000, v154
	global_load_dwordx4 v[0:3], v[162:163], off offset:384
	global_load_dwordx4 v[4:7], v[160:161], off offset:384
	global_load_dwordx4 v[8:11], v[158:159], off offset:384
	global_load_dwordx4 v[12:15], v[156:157], off offset:384
	global_load_dwordx4 v[16:19], v[154:155], off offset:384
	v_addc_co_u32_e32 v21, vcc, 0, v155, vcc
	v_add_co_u32_e32 v24, vcc, 0x58000, v154
	s_nop 1
	v_addc_co_u32_e32 v25, vcc, 0, v155, vcc
	v_add_co_u32_e32 v32, vcc, 0x84000, v154
	global_load_dwordx4 v[20:23], v[20:21], off offset:384
	s_nop 0
	global_load_dwordx4 v[24:27], v[24:25], off offset:384
	v_addc_co_u32_e32 v33, vcc, 0, v155, vcc
	global_load_dwordx4 v[32:35], v[32:33], off offset:384
; template <bool ATRANS = false, bool SWAP = true>
; DEV void gemm_seg(f32x4 (&acc)[4][4], bf16_t* As, bf16_t* Bs, const bf16_t* A, const bf16_t* B, int lda, int ldb,
;                   int K, int arow_lo, int arow_hi) {
;     ...
;   GLOAD(0, 0);
;   GLOAD(1, 1);
;   STAB(0, 0);
;   GLOAD(0, 2);
;   for (int kt = 0; kt < nk; kt += 2) {
;     COMPUTE(kt);
;     STAB(1, kt + 1);
;     GLOAD(1, kt + 3);
;     if (kt + 1 >= nk) break;
;     COMPUTE(kt + 1);
;     STAB(0, kt + 2);
;     GLOAD(0, kt + 4);
.LBB0_876:
	s_setprio 1
	ds_read_b128 v[168:171], v137 offset:18432
	ds_read_b128 v[208:211], v139 offset:55296
	ds_read_b128 v[212:215], v139 offset:57344
	ds_read_b128 v[220:223], v139 offset:59392
	ds_read_b128 v[224:227], v139 offset:61440
	ds_read_b128 v[228:231], v137 offset:20480
	ds_read_b128 v[232:235], v137 offset:22528
	ds_read_b128 v[236:239], v137 offset:24576
	s_waitcnt lgkmcnt(6)
	v_mfma_f32_16x16x32_bf16 v[124:127], v[208:211], v[168:171], v[124:127]
	ds_read_b128 v[240:243], v164 offset:18432
	ds_read_b128 v[244:247], v165 offset:55296
	s_waitcnt lgkmcnt(7)
	v_mfma_f32_16x16x32_bf16 v[120:123], v[212:215], v[168:171], v[120:123]
	s_waitcnt lgkmcnt(6)
	v_mfma_f32_16x16x32_bf16 v[116:119], v[220:223], v[168:171], v[116:119]
	s_waitcnt lgkmcnt(5)
	v_mfma_f32_16x16x32_bf16 v[112:115], v[224:227], v[168:171], v[112:115]
	ds_read_b128 v[168:171], v165 offset:57344
	s_waitcnt lgkmcnt(5)
	v_mfma_f32_16x16x32_bf16 v[108:111], v[208:211], v[228:231], v[108:111]
	v_mfma_f32_16x16x32_bf16 v[104:107], v[212:215], v[228:231], v[104:107]
	v_mfma_f32_16x16x32_bf16 v[100:103], v[220:223], v[228:231], v[100:103]
	v_mfma_f32_16x16x32_bf16 v[96:99], v[224:227], v[228:231], v[96:99]
	ds_read_b128 v[228:231], v165 offset:59392
	s_waitcnt lgkmcnt(5)
	v_mfma_f32_16x16x32_bf16 v[92:95], v[208:211], v[232:235], v[92:95]
	v_mfma_f32_16x16x32_bf16 v[88:91], v[212:215], v[232:235], v[88:91]
	v_mfma_f32_16x16x32_bf16 v[84:87], v[220:223], v[232:235], v[84:87]
	v_mfma_f32_16x16x32_bf16 v[80:83], v[224:227], v[232:235], v[80:83]
	ds_read_b128 v[232:235], v165 offset:61440
	s_waitcnt lgkmcnt(5)
	v_mfma_f32_16x16x32_bf16 v[76:79], v[208:211], v[236:239], v[76:79]
	ds_read_b128 v[208:211], v164 offset:20480
	v_mfma_f32_16x16x32_bf16 v[72:75], v[212:215], v[236:239], v[72:75]
	ds_read_b128 v[212:215], v164 offset:22528
	v_mfma_f32_16x16x32_bf16 v[68:71], v[220:223], v[236:239], v[68:71]
	ds_read_b128 v[220:223], v164 offset:24576
	v_mfma_f32_16x16x32_bf16 v[64:67], v[224:227], v[236:239], v[64:67]
	s_waitcnt vmcnt(8)
	ds_write_b128 v133, v[28:31]
	s_waitcnt lgkmcnt(7)
	v_mfma_f32_16x16x32_bf16 v[124:127], v[244:247], v[240:243], v[124:127]
	s_waitcnt lgkmcnt(6)
	v_mfma_f32_16x16x32_bf16 v[120:123], v[168:171], v[240:243], v[120:123]
	ds_write_b128 v133, v[36:39] offset:4096
	s_waitcnt lgkmcnt(6)
	v_mfma_f32_16x16x32_bf16 v[116:119], v[228:231], v[240:243], v[116:119]
	s_waitcnt lgkmcnt(5)
	v_mfma_f32_16x16x32_bf16 v[112:115], v[232:235], v[240:243], v[112:115]
	ds_write_b128 v133, v[40:43] offset:8192
	s_waitcnt lgkmcnt(5)
	v_mfma_f32_16x16x32_bf16 v[108:111], v[244:247], v[208:211], v[108:111]
	v_mfma_f32_16x16x32_bf16 v[104:107], v[168:171], v[208:211], v[104:107]
	ds_write_b128 v133, v[44:47] offset:12288
	v_mfma_f32_16x16x32_bf16 v[100:103], v[228:231], v[208:211], v[100:103]
	v_mfma_f32_16x16x32_bf16 v[96:99], v[232:235], v[208:211], v[96:99]
	ds_write_b128 v133, v[48:51] offset:36864
	s_waitcnt lgkmcnt(6)
	v_mfma_f32_16x16x32_bf16 v[92:95], v[244:247], v[212:215], v[92:95]
	v_mfma_f32_16x16x32_bf16 v[88:91], v[168:171], v[212:215], v[88:91]
	ds_write_b128 v133, v[52:55] offset:40960
	v_mfma_f32_16x16x32_bf16 v[84:87], v[228:231], v[212:215], v[84:87]
	v_mfma_f32_16x16x32_bf16 v[80:83], v[232:235], v[212:215], v[80:83]
	ds_write_b128 v133, v[56:59] offset:45056
	s_waitcnt lgkmcnt(7)
	v_mfma_f32_16x16x32_bf16 v[76:79], v[244:247], v[220:223], v[76:79]
	v_mfma_f32_16x16x32_bf16 v[72:75], v[168:171], v[220:223], v[72:75]
	ds_write_b128 v133, v[60:63] offset:49152
	v_mfma_f32_16x16x32_bf16 v[68:71], v[228:231], v[220:223], v[68:71]
	v_mfma_f32_16x16x32_bf16 v[64:67], v[232:235], v[220:223], v[64:67]
	s_setprio 0
	s_cmp_gt_u32 s24, 41
	s_cselect_b64 s[0:1], -1, 0

; template <bool ATRANS = false, bool SWAP = true>
; DEV void gemm_seg(f32x4 (&acc)[4][4], bf16_t* As, bf16_t* Bs, const bf16_t* A, const bf16_t* B, int lda, int ldb,
;                   int K, int arow_lo, int arow_hi) {
;     ...
;   GLOAD(0, 0);
;   GLOAD(1, 1);
;   STAB(0, 0);
;   GLOAD(0, 2);
;   for (int kt = 0; kt < nk; kt += 2) {
;     COMPUTE(kt);
;     STAB(1, kt + 1);
;     GLOAD(1, kt + 3);
;     if (kt + 1 >= nk) break;
;     COMPUTE(kt + 1);
;     STAB(0, kt + 2);
;     GLOAD(0, kt + 4);
.Lvm_pleg_ok:
	s_setprio 1
	ds_read_b128 v[168:171], v137
	ds_read_b128 v[208:211], v139 offset:36864
	ds_read_b128 v[212:215], v139 offset:38912
	ds_read_b128 v[220:223], v139 offset:40960
	ds_read_b128 v[224:227], v139 offset:43008
	ds_read_b128 v[228:231], v137 offset:2048
	ds_read_b128 v[232:235], v137 offset:4096
	ds_read_b128 v[236:239], v137 offset:6144
	s_waitcnt lgkmcnt(6)
	v_mfma_f32_16x16x32_bf16 v[124:127], v[208:211], v[168:171], v[124:127]
	ds_read_b128 v[240:243], v164
	ds_read_b128 v[244:247], v165 offset:36864
	s_waitcnt lgkmcnt(7)
	v_mfma_f32_16x16x32_bf16 v[120:123], v[212:215], v[168:171], v[120:123]
	s_waitcnt lgkmcnt(6)
	v_mfma_f32_16x16x32_bf16 v[116:119], v[220:223], v[168:171], v[116:119]
	s_waitcnt lgkmcnt(5)
	v_mfma_f32_16x16x32_bf16 v[112:115], v[224:227], v[168:171], v[112:115]
	ds_read_b128 v[168:171], v165 offset:38912
	s_waitcnt lgkmcnt(5)
	v_mfma_f32_16x16x32_bf16 v[108:111], v[208:211], v[228:231], v[108:111]
	v_mfma_f32_16x16x32_bf16 v[104:107], v[212:215], v[228:231], v[104:107]
	v_mfma_f32_16x16x32_bf16 v[100:103], v[220:223], v[228:231], v[100:103]
	v_mfma_f32_16x16x32_bf16 v[96:99], v[224:227], v[228:231], v[96:99]
	ds_read_b128 v[228:231], v165 offset:40960
	s_waitcnt lgkmcnt(5)
	v_mfma_f32_16x16x32_bf16 v[92:95], v[208:211], v[232:235], v[92:95]
	v_mfma_f32_16x16x32_bf16 v[88:91], v[212:215], v[232:235], v[88:91]
	v_mfma_f32_16x16x32_bf16 v[84:87], v[220:223], v[232:235], v[84:87]
	v_mfma_f32_16x16x32_bf16 v[80:83], v[224:227], v[232:235], v[80:83]
	ds_read_b128 v[232:235], v165 offset:43008
	s_waitcnt lgkmcnt(5)
	v_mfma_f32_16x16x32_bf16 v[76:79], v[208:211], v[236:239], v[76:79]
	ds_read_b128 v[208:211], v164 offset:2048
	v_mfma_f32_16x16x32_bf16 v[72:75], v[212:215], v[236:239], v[72:75]
	ds_read_b128 v[212:215], v164 offset:4096
	v_mfma_f32_16x16x32_bf16 v[68:71], v[220:223], v[236:239], v[68:71]
	ds_read_b128 v[220:223], v164 offset:6144
	v_mfma_f32_16x16x32_bf16 v[64:67], v[224:227], v[236:239], v[64:67]
	s_waitcnt vmcnt(8)
	ds_write_b128 v133, v[0:3] offset:18432
	s_waitcnt lgkmcnt(7)
	v_mfma_f32_16x16x32_bf16 v[124:127], v[244:247], v[240:243], v[124:127]
	s_waitcnt lgkmcnt(6)
	v_mfma_f32_16x16x32_bf16 v[120:123], v[168:171], v[240:243], v[120:123]
	ds_write_b128 v133, v[4:7] offset:22528
	s_waitcnt lgkmcnt(6)
	v_mfma_f32_16x16x32_bf16 v[116:119], v[228:231], v[240:243], v[116:119]
	s_waitcnt lgkmcnt(5)
	v_mfma_f32_16x16x32_bf16 v[112:115], v[232:235], v[240:243], v[112:115]
	ds_write_b128 v133, v[8:11] offset:26624
	s_waitcnt lgkmcnt(5)
	v_mfma_f32_16x16x32_bf16 v[108:111], v[244:247], v[208:211], v[108:111]
	v_mfma_f32_16x16x32_bf16 v[104:107], v[168:171], v[208:211], v[104:107]
	ds_write_b128 v133, v[12:15] offset:30720
	v_mfma_f32_16x16x32_bf16 v[100:103], v[228:231], v[208:211], v[100:103]
	v_mfma_f32_16x16x32_bf16 v[96:99], v[232:235], v[208:211], v[96:99]
	ds_write_b128 v133, v[16:19] offset:55296
	s_waitcnt lgkmcnt(6)
	v_mfma_f32_16x16x32_bf16 v[92:95], v[244:247], v[212:215], v[92:95]
	v_mfma_f32_16x16x32_bf16 v[88:91], v[168:171], v[212:215], v[88:91]
	ds_write_b128 v133, v[20:23] offset:59392
	v_mfma_f32_16x16x32_bf16 v[84:87], v[228:231], v[212:215], v[84:87]
	v_mfma_f32_16x16x32_bf16 v[80:83], v[232:235], v[212:215], v[80:83]
	ds_write_b128 v133, v[24:27] offset:63488
	s_waitcnt lgkmcnt(7)
	v_mfma_f32_16x16x32_bf16 v[76:79], v[244:247], v[220:223], v[76:79]
	v_mfma_f32_16x16x32_bf16 v[72:75], v[168:171], v[220:223], v[72:75]
	ds_write_b128 v135, v[32:35] offset:12288
	v_mfma_f32_16x16x32_bf16 v[68:71], v[228:231], v[220:223], v[68:71]
	v_mfma_f32_16x16x32_bf16 v[64:67], v[232:235], v[220:223], v[64:67]
	s_setprio 0
	s_cmp_gt_u32 s22, 12
	v_lshl_add_u64 v[162:163], v[144:145], 0, v[128:129]
	v_lshl_add_u64 v[160:161], v[146:147], 0, v[128:129]
	v_lshl_add_u64 v[158:159], v[148:149], 0, v[128:129]
	v_lshl_add_u64 v[156:157], v[150:151], 0, v[128:129]
	v_lshl_add_u64 v[154:155], v[152:153], 0, v[128:129]
	s_waitcnt lgkmcnt(0)
	s_barrier
	s_cbranch_scc1 .LBB0_926
	v_add_co_u32_e32 v20, vcc, 0x10000, v154
	global_load_dwordx4 v[0:3], v[162:163], off offset:384
	global_load_dwordx4 v[4:7], v[160:161], off offset:384
	global_load_dwordx4 v[8:11], v[158:159], off offset:384
	global_load_dwordx4 v[12:15], v[156:157], off offset:384
	global_load_dwordx4 v[16:19], v[154:155], off offset:384
	v_addc_co_u32_e32 v21, vcc, 0, v155, vcc
	v_add_co_u32_e32 v24, vcc, 0x20000, v154
	s_nop 1
	v_addc_co_u32_e32 v25, vcc, 0, v155, vcc
	v_add_co_u32_e32 v32, vcc, 0x30000, v154
	global_load_dwordx4 v[20:23], v[20:21], off offset:384
	s_nop 0
	global_load_dwordx4 v[24:27], v[24:25], off offset:384
	v_addc_co_u32_e32 v33, vcc, 0, v155, vcc
	global_load_dwordx4 v[32:35], v[32:33], off offset:384
; template <bool ATRANS = false, bool SWAP = true>
; DEV void gemm_seg(f32x4 (&acc)[4][4], bf16_t* As, bf16_t* Bs, const bf16_t* A, const bf16_t* B, int lda, int ldb,
;                   int K, int arow_lo, int arow_hi) {
;     ...
;   GLOAD(0, 0);
;   GLOAD(1, 1);
;   STAB(0, 0);
;   GLOAD(0, 2);
;   for (int kt = 0; kt < nk; kt += 2) {
;     COMPUTE(kt);
;     STAB(1, kt + 1);
;     GLOAD(1, kt + 3);
;     if (kt + 1 >= nk) break;
;     COMPUTE(kt + 1);
;     STAB(0, kt + 2);
;     GLOAD(0, kt + 4);
.LBB0_926:
	s_setprio 1
	ds_read_b128 v[168:171], v137 offset:18432
	ds_read_b128 v[208:211], v139 offset:55296
	ds_read_b128 v[212:215], v139 offset:57344
	ds_read_b128 v[220:223], v139 offset:59392
	ds_read_b128 v[224:227], v139 offset:61440
	ds_read_b128 v[228:231], v137 offset:20480
	ds_read_b128 v[232:235], v137 offset:22528
	ds_read_b128 v[236:239], v137 offset:24576
	s_waitcnt lgkmcnt(6)
	v_mfma_f32_16x16x32_bf16 v[124:127], v[208:211], v[168:171], v[124:127]
	ds_read_b128 v[240:243], v164 offset:18432
	ds_read_b128 v[244:247], v165 offset:55296
	s_waitcnt lgkmcnt(7)
	v_mfma_f32_16x16x32_bf16 v[120:123], v[212:215], v[168:171], v[120:123]
	s_waitcnt lgkmcnt(6)
	v_mfma_f32_16x16x32_bf16 v[116:119], v[220:223], v[168:171], v[116:119]
	s_waitcnt lgkmcnt(5)
	v_mfma_f32_16x16x32_bf16 v[112:115], v[224:227], v[168:171], v[112:115]
	ds_read_b128 v[168:171], v165 offset:57344
	s_waitcnt lgkmcnt(5)
	v_mfma_f32_16x16x32_bf16 v[108:111], v[208:211], v[228:231], v[108:111]
	v_mfma_f32_16x16x32_bf16 v[104:107], v[212:215], v[228:231], v[104:107]
	v_mfma_f32_16x16x32_bf16 v[100:103], v[220:223], v[228:231], v[100:103]
	v_mfma_f32_16x16x32_bf16 v[96:99], v[224:227], v[228:231], v[96:99]
	ds_read_b128 v[228:231], v165 offset:59392
	s_waitcnt lgkmcnt(5)
	v_mfma_f32_16x16x32_bf16 v[92:95], v[208:211], v[232:235], v[92:95]
	v_mfma_f32_16x16x32_bf16 v[88:91], v[212:215], v[232:235], v[88:91]
	v_mfma_f32_16x16x32_bf16 v[84:87], v[220:223], v[232:235], v[84:87]
	v_mfma_f32_16x16x32_bf16 v[80:83], v[224:227], v[232:235], v[80:83]
	ds_read_b128 v[232:235], v165 offset:61440
	s_waitcnt lgkmcnt(5)
	v_mfma_f32_16x16x32_bf16 v[76:79], v[208:211], v[236:239], v[76:79]
	ds_read_b128 v[208:211], v164 offset:20480
	v_mfma_f32_16x16x32_bf16 v[72:75], v[212:215], v[236:239], v[72:75]
	ds_read_b128 v[212:215], v164 offset:22528
	v_mfma_f32_16x16x32_bf16 v[68:71], v[220:223], v[236:239], v[68:71]
	ds_read_b128 v[220:223], v164 offset:24576
	v_mfma_f32_16x16x32_bf16 v[64:67], v[224:227], v[236:239], v[64:67]
	s_waitcnt vmcnt(8)
	ds_write_b128 v133, v[28:31]
	s_waitcnt lgkmcnt(7)
	v_mfma_f32_16x16x32_bf16 v[124:127], v[244:247], v[240:243], v[124:127]
	s_waitcnt lgkmcnt(6)
	v_mfma_f32_16x16x32_bf16 v[120:123], v[168:171], v[240:243], v[120:123]
	ds_write_b128 v133, v[36:39] offset:4096
	s_waitcnt lgkmcnt(6)
	v_mfma_f32_16x16x32_bf16 v[116:119], v[228:231], v[240:243], v[116:119]
	s_waitcnt lgkmcnt(5)
	v_mfma_f32_16x16x32_bf16 v[112:115], v[232:235], v[240:243], v[112:115]
	ds_write_b128 v133, v[40:43] offset:8192
	s_waitcnt lgkmcnt(5)
	v_mfma_f32_16x16x32_bf16 v[108:111], v[244:247], v[208:211], v[108:111]
	v_mfma_f32_16x16x32_bf16 v[104:107], v[168:171], v[208:211], v[104:107]
	ds_write_b128 v133, v[44:47] offset:12288
	v_mfma_f32_16x16x32_bf16 v[100:103], v[228:231], v[208:211], v[100:103]
	v_mfma_f32_16x16x32_bf16 v[96:99], v[232:235], v[208:211], v[96:99]
	ds_write_b128 v133, v[48:51] offset:36864
	s_waitcnt lgkmcnt(6)
	v_mfma_f32_16x16x32_bf16 v[92:95], v[244:247], v[212:215], v[92:95]
	v_mfma_f32_16x16x32_bf16 v[88:91], v[168:171], v[212:215], v[88:91]
	ds_write_b128 v133, v[52:55] offset:40960
	v_mfma_f32_16x16x32_bf16 v[84:87], v[228:231], v[212:215], v[84:87]
	v_mfma_f32_16x16x32_bf16 v[80:83], v[232:235], v[212:215], v[80:83]
	ds_write_b128 v133, v[56:59] offset:45056
	s_waitcnt lgkmcnt(7)
	v_mfma_f32_16x16x32_bf16 v[76:79], v[244:247], v[220:223], v[76:79]
	v_mfma_f32_16x16x32_bf16 v[72:75], v[168:171], v[220:223], v[72:75]
	ds_write_b128 v133, v[60:63] offset:49152
	v_mfma_f32_16x16x32_bf16 v[68:71], v[228:231], v[220:223], v[68:71]
	v_mfma_f32_16x16x32_bf16 v[64:67], v[232:235], v[220:223], v[64:67]
	s_setprio 0
	s_cmp_gt_u32 s22, 13
	s_cselect_b64 s[0:1], -1, 0
